# baseline (speedup 1.0000x reference)
; #define SLOADP(i, Kp, Vp, t) do { const char* kp = (const char*)(Kp) + (long)(t) * (64 * 192); const char* vp = (const char*)(Vp) + (long)(t) * (64 * 128); \
;     sr_[i].k0 = *reinterpret_cast<const bf16x8*>(kp + kc0 * 16); sr_[i].k1 = *reinterpret_cast<const bf16x8*>(kp + kc1 * 16); \
;     sr_[i].v0 = *reinterpret_cast<const bf16x8*>(vp + tid * 16); } while (0)
; #define SWRITE(b, i) do { *(bf16x8*)(V_lds + (b) * SHM_VT + vst) = sr_[i].v0; \
;     *(bf16x8*)(K_lds + (b) * SHM_KT + kst0) = sr_[i].k0; *(bf16x8*)(K_lds + (b) * SHM_KT + kst1) = sr_[i].k1; } while (0)
; __device__ __forceinline__ void partialSM(f32x16& p0, f32x16& p1, float& m_reg, float& mn, float& alpha) {
;   constexpr float C = ATT_SCALE * 1.4426950408889634f;
;   float pmax = p0[0];
;   #pragma unroll
;   for (int r = 1; r < 16; ++r) pmax = fmaxf(pmax, p0[r]);
;   #pragma unroll
;   for (int r = 0; r < 16; ++r) pmax = fmaxf(pmax, p1[r]);
;   { auto rr = __builtin_amdgcn_permlane32_swap(__float_as_uint(pmax), __float_as_uint(pmax), false, false);
;     pmax = fmaxf(__uint_as_float(rr[0]), __uint_as_float(rr[1])); }
;   if (__builtin_expect(__all(pmax - m_reg <= THR / ATT_SCALE), 1)) { mn = m_reg; alpha = 1.f; }
;   else { mn = fmaxf(m_reg, pmax); alpha = __builtin_amdgcn_exp2f((m_reg - mn) * C); m_reg = mn; }
;   float mnC = -mn * C;
;   #pragma unroll
;   for (int r = 0; r < 16; ++r) p0[r] = fmaf(p0[r], C, mnC);
;   #pragma unroll
;   for (int r = 0; r < 16; ++r) p1[r] = fmaf(p1[r], C, mnC);
;   #pragma unroll
;   for (int r = 0; r < 16; ++r) p0[r] = __builtin_amdgcn_exp2f(p0[r]);
; __device__ __forceinline__ void attn_phase(const bf16* __restrict__ qbase, const bf16* __restrict__ Kbase, const bf16* __restrict__ Vbase, bf16* __restrict__ mixbase) {
;     ...
;     float m_reg = -1e30f; f32x16 o[2] = {}, o2 = {};
;     f32x16 pA0, pA1, pB0, pB1; float mnA, mnB, alA, alB; bf16x8 pa0, pa1, pa2, pa3;
;     __syncthreads();
;     SWRITE(0, SO); __syncthreads();
;     qkt(pA0, pA1, K_lds, qr, r32, hi); partialSM(pA0, pA1, m_reg, mnA, alA);
;     SWRITE(1, SE); SLOADP(SE, Kh, Vh, 2); __syncthreads();
.LBB0_512:
	s_barrier
	s_waitcnt vmcnt(35)
	ds_write_b128 v216, v[136:139]
	ds_write_b128 v217, v[132:135] offset:16384
	ds_write_b128 v218, v[140:143] offset:16384
	s_waitcnt lgkmcnt(0)
	s_barrier
	ds_read_b128 v[0:3], v219 offset:16384
	ds_read_b128 v[4:7], v219 offset:16416
	s_waitcnt lgkmcnt(1)
	v_mfma_f32_32x32x16_bf16 v[32:47], v[0:3], v[80:83], 0
	ds_read_b128 v[0:3], v219 offset:23040
	ds_read_b128 v[8:11], v219 offset:23072
	s_mov_b32 s41, s40
	s_mov_b32 s42, s40
	s_mov_b32 s43, s40
	s_mov_b32 s44, s40
	s_mov_b32 s45, s40
	s_mov_b32 s46, s40
	s_waitcnt lgkmcnt(2)
	v_mfma_f32_32x32x16_bf16 v[32:47], v[4:7], v[84:87], v[32:47]
	s_mov_b32 s47, s40
	s_mov_b32 s48, s40
	s_mov_b32 s49, s40
	s_mov_b32 s50, s40
	s_mov_b32 s51, s40
	s_mov_b32 s52, s40
	s_mov_b32 s53, s40
	s_waitcnt lgkmcnt(1)
	v_mfma_f32_32x32x16_bf16 v[16:31], v[0:3], v[80:83], 0
	ds_read_b128 v[0:3], v219 offset:16448
	ds_read_b128 v[4:7], v219 offset:16480
	s_mov_b32 s54, s40
	s_mov_b32 s55, s40
	v_lshl_add_u64 v[182:183], s[30:31], 0, v[160:161]
	v_lshl_add_u64 v[184:185], s[28:29], 0, v[166:167]
	v_lshl_add_u64 v[186:187], s[28:29], 0, v[160:161]
	v_lshl_add_u64 v[188:189], v[48:49], 0, v[164:165]
	s_waitcnt lgkmcnt(1)
	v_mfma_f32_32x32x16_bf16 v[32:47], v[0:3], v[88:91], v[32:47]
	v_lshl_add_u64 v[190:191], v[182:183], 0, s[10:11]
	v_lshl_add_u64 v[198:199], s[60:61], 0, v[176:177]
	v_lshl_add_u64 v[200:201], s[6:7], 0, v[160:161]
	v_lshl_add_u64 v[202:203], s[6:7], 0, v[178:179]
	v_mfma_f32_32x32x16_bf16 v[16:31], v[8:11], v[84:87], v[16:31]
	ds_read_b128 v[0:3], v219 offset:23104
	ds_read_b128 v[8:11], v219 offset:23136
	s_waitcnt lgkmcnt(2)
	v_mfma_f32_32x32x16_bf16 v[32:47], v[4:7], v[92:95], v[32:47]
	s_waitcnt lgkmcnt(1)
	v_mfma_f32_32x32x16_bf16 v[16:31], v[0:3], v[88:91], v[16:31]
	ds_read_b128 v[0:3], v219 offset:16512
	ds_read_b128 v[4:7], v219 offset:16544
	s_waitcnt lgkmcnt(1)
	v_mfma_f32_32x32x16_bf16 v[32:47], v[0:3], v[96:99], v[32:47]
	v_mfma_f32_32x32x16_bf16 v[16:31], v[8:11], v[92:95], v[16:31]
	s_waitcnt lgkmcnt(0)
	v_mfma_f32_32x32x16_bf16 v[32:47], v[4:7], v[100:103], v[32:47]
	ds_read_b128 v[0:3], v219 offset:23168
	ds_read_b128 v[4:7], v219 offset:23200
	s_waitcnt vmcnt(32)
	ds_write_b128 v216, v[112:115] offset:8192
	ds_write_b128 v217, v[104:107] offset:29696
	ds_write_b128 v218, v[108:111] offset:29696
	s_nop 5
	v_max_f32_e32 v8, v33, v33
	s_waitcnt lgkmcnt(4)
	v_mfma_f32_32x32x16_bf16 v[16:31], v[0:3], v[96:99], v[16:31]
	v_max_f32_e32 v9, v32, v32
	v_max_f32_e32 v8, v9, v8
	v_max3_f32 v0, v8, v34, v35
	v_max3_f32 v0, v0, v36, v37
	v_max3_f32 v0, v0, v38, v39
	v_max3_f32 v0, v0, v40, v41
	v_max3_f32 v0, v0, v42, v43
	s_waitcnt lgkmcnt(3)
	v_mfma_f32_32x32x16_bf16 v[16:31], v[4:7], v[100:103], v[16:31]
	v_max3_f32 v0, v0, v44, v45
	v_max3_f32 v0, v0, v46, v47
	s_nop 9
	v_max3_f32 v0, v0, v16, v17
	v_max3_f32 v0, v0, v18, v19
	v_max3_f32 v0, v0, v20, v21
	v_max3_f32 v0, v0, v22, v23
	v_max3_f32 v0, v0, v24, v25
	v_max3_f32 v0, v0, v26, v27
	v_max3_f32 v0, v0, v28, v29
	v_max3_f32 v0, v0, v30, v31
	v_mov_b32_e32 v1, v0
	s_nop 1
	v_permlane32_swap_b32_e32 v0, v1
	v_max_f32_e32 v1, v1, v1
	v_max_f32_e32 v0, v0, v0
	v_max_f32_e32 v0, v0, v1
	v_add_f32_e32 v1, 0x7149f2ca, v0
	v_cmp_ge_f32_e32 vcc, s9, v1
	s_cmp_lg_u64 vcc, exec
	s_cselect_b64 vcc, -1, 0
	s_add_u32 s0, s6, 0x6000
	s_addc_u32 s1, s7, 0
	v_max_f32_e32 v50, 0xf149f2ca, v0
	v_lshl_add_u64 v[0:1], s[0:1], 0, v[160:161]
	v_lshl_add_u64 v[2:3], s[0:1], 0, v[166:167]
	global_load_dwordx4 v[104:107], v[0:1], off
	global_load_dwordx4 v[108:111], v[2:3], off
	v_lshl_add_u64 v[0:1], s[60:61], 0, v[160:161]
	v_add_co_u32_e64 v0, s[0:1], s12, v0
	v_cndmask_b32_e32 v181, v220, v50, vcc
	s_nop 0
	v_addc_co_u32_e64 v1, s[0:1], 0, v1, s[0:1]
	global_load_dwordx4 v[112:115], v[0:1], off
	v_mul_f32_e32 v50, 0xbe16c740, v181
	v_mov_b32_e32 v51, v50
	v_fmamk_f32 v32, v32, 0x3e16c740, v50
	v_fmamk_f32 v33, v33, 0x3e16c740, v50
	v_fmamk_f32 v34, v34, 0x3e16c740, v50
	v_fmamk_f32 v35, v35, 0x3e16c740, v50
	v_fmamk_f32 v36, v36, 0x3e16c740, v50
	v_fmamk_f32 v37, v37, 0x3e16c740, v50
	v_fmamk_f32 v38, v38, 0x3e16c740, v50
	v_fmamk_f32 v39, v39, 0x3e16c740, v50
	v_fmamk_f32 v40, v40, 0x3e16c740, v50
	v_fmamk_f32 v41, v41, 0x3e16c740, v50
	v_fmamk_f32 v42, v42, 0x3e16c740, v50
	v_fmamk_f32 v43, v43, 0x3e16c740, v50
	v_fmamk_f32 v44, v44, 0x3e16c740, v50
	v_fmamk_f32 v45, v45, 0x3e16c740, v50
	v_fmamk_f32 v46, v46, 0x3e16c740, v50
	v_fmac_f32_e32 v51, 0x3e16c740, v47
	v_mov_b64_e32 v[0:1], s[40:41]
	v_exp_f32_e32 v226, v32
	v_exp_f32_e32 v230, v33
	v_exp_f32_e32 v227, v34
	v_exp_f32_e32 v231, v35
	v_exp_f32_e32 v228, v36
	v_exp_f32_e32 v232, v37
	v_exp_f32_e32 v225, v38
	v_exp_f32_e32 v229, v39
	v_exp_f32_e32 v206, v40
	v_exp_f32_e32 v223, v41
	v_exp_f32_e32 v207, v42
	v_exp_f32_e32 v224, v43
	v_exp_f32_e32 v205, v44
	v_exp_f32_e32 v222, v45
	v_exp_f32_e32 v204, v46
	v_exp_f32_e32 v221, v51
	v_mov_b64_e32 v[14:15], s[54:55]
	s_add_u32 s0, s28, 0x3000
	v_mov_b64_e32 v[2:3], s[42:43]
	v_mov_b64_e32 v[4:5], s[44:45]
	v_mov_b64_e32 v[6:7], s[46:47]
	v_mov_b64_e32 v[8:9], s[48:49]
	v_mov_b64_e32 v[10:11], s[50:51]
	v_mov_b64_e32 v[12:13], s[52:53]
	v_pk_fma_f32 v[154:155], v[30:31], s[2:3], v[50:51] op_sel_hi:[1,0,0]
	v_pk_fma_f32 v[156:157], v[28:29], s[2:3], v[50:51] op_sel_hi:[1,0,0]
	v_pk_fma_f32 v[158:159], v[26:27], s[2:3], v[50:51] op_sel_hi:[1,0,0]
	v_pk_fma_f32 v[144:145], v[24:25], s[2:3], v[50:51] op_sel_hi:[1,0,0]
	v_pk_fma_f32 v[146:147], v[22:23], s[2:3], v[50:51] op_sel_hi:[1,0,0]
	v_pk_fma_f32 v[148:149], v[20:21], s[2:3], v[50:51] op_sel_hi:[1,0,0]
	v_pk_fma_f32 v[150:151], v[18:19], s[2:3], v[50:51] op_sel_hi:[1,0,0]
	v_pk_fma_f32 v[152:153], v[16:17], s[2:3], v[50:51] op_sel_hi:[1,0,0]
	s_addc_u32 s1, s29, 0
	v_mov_b64_e32 v[30:31], v[14:15]
	v_mov_b64_e32 v[46:47], v[14:15]
	s_mov_b32 s41, 1
	v_lshl_add_u64 v[194:195], s[0:1], 0, v[166:167]
	v_lshl_add_u64 v[196:197], s[0:1], 0, v[160:161]
	s_mov_b64 s[42:43], 0
	v_mov_b64_e32 v[28:29], v[12:13]
	v_mov_b64_e32 v[26:27], v[10:11]
	v_mov_b64_e32 v[24:25], v[8:9]
	v_mov_b64_e32 v[22:23], v[6:7]
	v_mov_b64_e32 v[20:21], v[4:5]
	v_mov_b64_e32 v[18:19], v[2:3]
	v_mov_b64_e32 v[16:17], v[0:1]
	v_mov_b64_e32 v[44:45], v[12:13]
	v_mov_b64_e32 v[42:43], v[10:11]
	v_mov_b64_e32 v[40:41], v[8:9]
	v_mov_b64_e32 v[38:39], v[6:7]
	v_mov_b64_e32 v[36:37], v[4:5]
	v_mov_b64_e32 v[34:35], v[2:3]
	v_mov_b64_e32 v[32:33], v[0:1]
	s_waitcnt lgkmcnt(0)
; #define SBAR() __builtin_amdgcn_sched_barrier(0)
; #define SLOADP(i, Kp, Vp, t) do { const char* kp = (const char*)(Kp) + (long)(t) * (64 * 192); const char* vp = (const char*)(Vp) + (long)(t) * (64 * 128); \
;     sr_[i].k0 = *reinterpret_cast<const bf16x8*>(kp + kc0 * 16); sr_[i].k1 = *reinterpret_cast<const bf16x8*>(kp + kc1 * 16); \
;     sr_[i].v0 = *reinterpret_cast<const bf16x8*>(vp + tid * 16); } while (0)
; __device__ __forceinline__ void finishSM(f32x16& p0, f32x16& p1, bf16x8& pa0, bf16x8& pa1, bf16x8& pa2, bf16x8& pa3) {
;   #pragma unroll
;   for (int r = 0; r < 16; ++r) p1[r] = __builtin_amdgcn_exp2f(p1[r]);
;     ...
;   PK4(p0, 0, pa0); PK4(p0, 8, pa1); PK4(p1, 0, pa2); PK4(p1, 8, pa3);
;     ...
; }
; __device__ __forceinline__ void qkt(f32x16& p0, f32x16& p1, const char* Ks, const bf16x8* qr, int r32, int hi) {
;   p0 = f32x16{}; p1 = f32x16{};
;   #pragma unroll
;   for (int d0 = 0; d0 < 6; ++d0) { int cb = (d0 * 16 + hi * 8) * 2;
;     bf16x8 b0 = *reinterpret_cast<const bf16x8*>(Ks + r32 * KPITCH + cb);
;     bf16x8 b1 = *reinterpret_cast<const bf16x8*>(Ks + (32 + r32) * KPITCH + cb);
;     p0 = __builtin_amdgcn_mfma_f32_32x32x16_bf16(b0, qr[d0], p0, 0, 0, 0);
;     p1 = __builtin_amdgcn_mfma_f32_32x32x16_bf16(b1, qr[d0], p1, 0, 0, 0); }
; __device__ __forceinline__ void attn_phase(const bf16* __restrict__ qbase, const bf16* __restrict__ Kbase, const bf16* __restrict__ Vbase, bf16* __restrict__ mixbase) {
;     ...
;       SBAR(); qkt(pB0, pB1, K_lds + SHM_KT, qr, r32, hi);
;       finishSM(pA0, pA1, pa0, pa1, pa2, pa3); SBAR();
;       if (j + 2 < NT) SLOADP(SO, Kh, Vh, j + 2); else if (has_next) SLOADP(SO, Kn, Vn, 0);
.Latt_head:
	s_barrier
.LBB0_513:
	ds_read_b128 v[48:51], v219 offset:29696
	ds_read_b128 v[120:123], v219 offset:29728
	v_exp_f32_e32 v152, v152
	v_exp_f32_e32 v153, v153
	v_exp_f32_e32 v158, v158
	s_waitcnt lgkmcnt(1)
	v_mfma_f32_32x32x16_bf16 v[64:79], v[48:51], v[80:83], 0
	ds_read_b128 v[48:51], v219 offset:36352
	ds_read_b128 v[124:127], v219 offset:36384
	v_exp_f32_e32 v159, v159
	v_exp_f32_e32 v208, v150
	v_exp_f32_e32 v209, v151
	v_exp_f32_e32 v233, v148
	v_exp_f32_e32 v250, v145
	s_waitcnt lgkmcnt(1)
	v_mfma_f32_32x32x16_bf16 v[48:63], v[48:51], v[80:83], 0
	v_mfma_f32_32x32x16_bf16 v[64:79], v[120:123], v[84:87], v[64:79]
	s_waitcnt lgkmcnt(0)
	v_mfma_f32_32x32x16_bf16 v[48:63], v[124:127], v[84:87], v[48:63]
	ds_read_b128 v[120:123], v219 offset:29760
	ds_read_b128 v[124:127], v219 offset:29792
	ds_read_b128 v[128:131], v219 offset:36416
	ds_read_b128 v[234:237], v219 offset:36448
	ds_read_b128 v[238:241], v219 offset:29824
	ds_read_b128 v[242:245], v219 offset:29856
	s_waitcnt lgkmcnt(5)
	v_mfma_f32_32x32x16_bf16 v[64:79], v[120:123], v[88:91], v[64:79]
	ds_read_b128 v[120:123], v219 offset:36480
	ds_read_b128 v[246:249], v219 offset:36512
	v_cvt_pk_bf16_f32 v148, v226, v230
	s_waitcnt lgkmcnt(5)
	v_mfma_f32_32x32x16_bf16 v[48:63], v[128:131], v[88:91], v[48:63]
	v_exp_f32_e32 v128, v149
	v_exp_f32_e32 v129, v146
	v_exp_f32_e32 v130, v147
	v_exp_f32_e32 v131, v144
	v_cvt_pk_bf16_f32 v149, v227, v231
	v_cvt_pk_bf16_f32 v150, v228, v232
	v_cvt_pk_bf16_f32 v151, v225, v229
	v_mfma_f32_32x32x16_bf16 v[64:79], v[124:127], v[92:95], v[64:79]
	v_exp_f32_e32 v124, v156
	v_exp_f32_e32 v125, v157
	v_exp_f32_e32 v126, v154
	v_exp_f32_e32 v127, v155
	v_cvt_pk_bf16_f32 v144, v206, v223
	v_cvt_pk_bf16_f32 v145, v207, v224
	v_cvt_pk_bf16_f32 v146, v205, v222
	s_waitcnt lgkmcnt(4)
	v_mfma_f32_32x32x16_bf16 v[48:63], v[234:237], v[92:95], v[48:63]
	v_cvt_pk_bf16_f32 v147, v204, v221
	v_cvt_pk_bf16_f32 v152, v152, v153
	v_cvt_pk_bf16_f32 v153, v208, v209
	v_cvt_pk_bf16_f32 v154, v233, v128
	v_cvt_pk_bf16_f32 v155, v129, v130
	v_cvt_pk_bf16_f32 v156, v131, v250
	v_cvt_pk_bf16_f32 v157, v158, v159
	s_waitcnt lgkmcnt(3)
	v_mfma_f32_32x32x16_bf16 v[64:79], v[238:241], v[96:99], v[64:79]
	v_cvt_pk_bf16_f32 v158, v124, v125
	v_cvt_pk_bf16_f32 v159, v126, v127
	v_permlane32_swap_b32_e32 v148, v150
	v_permlane32_swap_b32_e32 v149, v151
	v_permlane32_swap_b32_e32 v144, v146
	s_waitcnt lgkmcnt(1)
	v_mfma_f32_32x32x16_bf16 v[48:63], v[120:123], v[96:99], v[48:63]
	v_permlane32_swap_b32_e32 v145, v147
	v_permlane32_swap_b32_e32 v152, v154
	v_permlane32_swap_b32_e32 v153, v155
	v_permlane32_swap_b32_e32 v156, v158
	v_mfma_f32_32x32x16_bf16 v[64:79], v[242:245], v[100:103], v[64:79]
	v_permlane32_swap_b32_e32 v157, v159
	s_waitcnt lgkmcnt(0)
	v_mfma_f32_32x32x16_bf16 v[48:63], v[246:249], v[100:103], v[48:63]
	s_cmp_eq_u32 s42, 0x5a000
	s_cselect_b64 s[46:47], -1, 0
	s_cmp_lg_u32 s42, 0x5a000
	s_cselect_b64 s[44:45], -1, 0
	s_mov_b64 s[0:1], -1
	s_and_b64 vcc, exec, s[46:47]
	v_lshl_add_u64 v[206:207], v[200:201], 0, s[42:43]
	v_lshl_add_u64 v[204:205], v[202:203], 0, s[42:43]
	s_cbranch_vccnz .LBB0_515
	v_add_co_u32_e32 v120, vcc, 0x9000, v206
	s_mov_b64 s[0:1], 0
	s_nop 0
	v_addc_co_u32_e32 v121, vcc, 0, v207, vcc
	v_add_co_u32_e32 v124, vcc, 0xb000, v204
	s_nop 1
	v_addc_co_u32_e32 v125, vcc, 0, v205, vcc
	v_add_co_u32_e32 v128, vcc, 0xffffe000, v198
	global_load_dwordx4 v[120:123], v[120:121], off
	s_nop 0
	global_load_dwordx4 v[124:127], v[124:125], off
	v_addc_co_u32_e32 v129, vcc, -1, v199, vcc
	global_load_dwordx4 v[128:131], v[128:129], off
.LBB0_515:
	s_andn2_b64 s[6:7], exec, s[74:75]
	s_andn2_b64 vcc, exec, s[0:1]
	s_cbranch_vccnz .LBB0_519
	s_and_b64 vcc, exec, s[6:7]
	s_cbranch_vccnz .LBB0_518
	global_load_dwordx4 v[132:135], v[186:187], off
	global_load_dwordx4 v[140:143], v[184:185], off
	global_load_dwordx4 v[136:139], v[182:183], off

; #define SWRITE(b, i) do { *(bf16x8*)(V_lds + (b) * SHM_VT + vst) = sr_[i].v0; \
;     *(bf16x8*)(K_lds + (b) * SHM_KT + kst0) = sr_[i].k0; *(bf16x8*)(K_lds + (b) * SHM_KT + kst1) = sr_[i].k1; } while (0)
; #define SWAIT() asm volatile("s_waitcnt vmcnt(3)" ::: "memory")
; #define RESC(a) do { if (__any((a) < 1.f)) { if (hi == 0) al_l[r32] = (a); asm volatile("s_waitcnt lgkmcnt(0)" ::: "memory"); \
;     _Pragma("unroll") for (int r = 0; r < 16; ++r) { const float a_ = al_l[crow(r, hi)]; o[0][r] *= a_; o[1][r] *= a_; o2[r] *= a_; } } } while (0)
; __device__ __forceinline__ void partialSM(f32x16& p0, f32x16& p1, float& m_reg, float& mn, float& alpha) {
;   constexpr float C = ATT_SCALE * 1.4426950408889634f;
;   float pmax = p0[0];
;   #pragma unroll
;   for (int r = 1; r < 16; ++r) pmax = fmaxf(pmax, p0[r]);
;   #pragma unroll
;   for (int r = 0; r < 16; ++r) pmax = fmaxf(pmax, p1[r]);
;   { auto rr = __builtin_amdgcn_permlane32_swap(__float_as_uint(pmax), __float_as_uint(pmax), false, false);
;     pmax = fmaxf(__uint_as_float(rr[0]), __uint_as_float(rr[1])); }
;   if (__builtin_expect(__all(pmax - m_reg <= THR / ATT_SCALE), 1)) { mn = m_reg; alpha = 1.f; }
;   else { mn = fmaxf(m_reg, pmax); alpha = __builtin_amdgcn_exp2f((m_reg - mn) * C); m_reg = mn; }
;   float mnC = -mn * C;
;   #pragma unroll
;   for (int r = 0; r < 16; ++r) p0[r] = fmaf(p0[r], C, mnC);
;   #pragma unroll
;   for (int r = 0; r < 16; ++r) p1[r] = fmaf(p1[r], C, mnC);
;   #pragma unroll
;   for (int r = 0; r < 16; ++r) p0[r] = __builtin_amdgcn_exp2f(p0[r]);
; __device__ __forceinline__ void attn_phase(const bf16* __restrict__ qbase, const bf16* __restrict__ Kbase, const bf16* __restrict__ Vbase, bf16* __restrict__ mixbase) {
;     ...
;       PVD(vb0 + SHM_VT); partialSM(pA0, pA1, m_reg, mnA, alA);
;       __syncthreads(); SWAIT(); if (j + 2 < NT) SWRITE(1, SO);
;       RESC(alA); __syncthreads();
.LBB0_539:
	v_cndmask_b32_e64 v181, v132, v148, s[0:1]
	v_mul_f32_e32 v132, 0xbe16c740, v181
	v_mov_b32_e32 v133, v132
	v_fmamk_f32 v48, v48, 0x3e16c740, v132
	v_fmamk_f32 v49, v49, 0x3e16c740, v132
	v_fmamk_f32 v50, v50, 0x3e16c740, v132
	v_fmamk_f32 v51, v51, 0x3e16c740, v132
	v_fmamk_f32 v52, v52, 0x3e16c740, v132
	v_fmamk_f32 v53, v53, 0x3e16c740, v132
	v_fmamk_f32 v54, v54, 0x3e16c740, v132
	v_fmamk_f32 v55, v55, 0x3e16c740, v132
	v_fmamk_f32 v56, v56, 0x3e16c740, v132
	v_fmamk_f32 v57, v57, 0x3e16c740, v132
	v_fmamk_f32 v58, v58, 0x3e16c740, v132
	v_fmamk_f32 v59, v59, 0x3e16c740, v132
	v_fmamk_f32 v60, v60, 0x3e16c740, v132
	v_fmamk_f32 v61, v61, 0x3e16c740, v132
	v_fmamk_f32 v62, v62, 0x3e16c740, v132
	v_fmac_f32_e32 v133, 0x3e16c740, v63
	v_exp_f32_e32 v226, v48
	v_exp_f32_e32 v230, v49
	v_exp_f32_e32 v227, v50
	v_exp_f32_e32 v231, v51
	v_exp_f32_e32 v228, v52
	v_exp_f32_e32 v232, v53
	v_exp_f32_e32 v225, v54
	v_exp_f32_e32 v229, v55
	v_exp_f32_e32 v206, v56
	v_exp_f32_e32 v223, v57
	v_exp_f32_e32 v207, v58
	v_exp_f32_e32 v224, v59
	v_exp_f32_e32 v205, v60
	v_exp_f32_e32 v222, v61
	v_exp_f32_e32 v204, v62
	v_exp_f32_e32 v221, v133
	s_add_i32 s41, s41, 2
	s_add_u32 s42, s42, 0x6000
	v_pk_fma_f32 v[152:153], v[64:65], s[2:3], v[132:133] op_sel_hi:[1,0,0]
	v_pk_fma_f32 v[150:151], v[66:67], s[2:3], v[132:133] op_sel_hi:[1,0,0]
	v_pk_fma_f32 v[148:149], v[68:69], s[2:3], v[132:133] op_sel_hi:[1,0,0]
	v_pk_fma_f32 v[146:147], v[70:71], s[2:3], v[132:133] op_sel_hi:[1,0,0]
	v_pk_fma_f32 v[144:145], v[72:73], s[2:3], v[132:133] op_sel_hi:[1,0,0]
	v_pk_fma_f32 v[158:159], v[74:75], s[2:3], v[132:133] op_sel_hi:[1,0,0]
	v_pk_fma_f32 v[156:157], v[76:77], s[2:3], v[132:133] op_sel_hi:[1,0,0]
	v_pk_fma_f32 v[154:155], v[78:79], s[2:3], v[132:133] op_sel_hi:[1,0,0]
	v_lshl_add_u64 v[198:199], v[198:199], 0, s[14:15]
	s_addc_u32 s43, s43, 0
	s_and_b64 vcc, exec, s[46:47]
	s_waitcnt lgkmcnt(0)
	s_cbranch_vccnz .Latt_exit
	s_branch .Latt_head
.Latt_exit:
	s_barrier
	s_branch .LBB0_509
